# v12 + grid barrier protocol B: last arriver of each XCD writes back L2 and bumps every XCD release word; all wait for (gen+1)*nx; TOP/TOPGEN hop removed
# baseline (speedup 1.0000x reference)
; __device__ __forceinline__ int ltid(int wave) { int t = (wave << 6) | (int)__builtin_amdgcn_mbcnt_hi(~0u, __builtin_amdgcn_mbcnt_lo(~0u, 0u)); asm volatile("" : "+v"(t)); return t; }
; __device__ __forceinline__ unsigned xb_ld(unsigned* p)              { return __hip_atomic_load(p, __ATOMIC_RELAXED, __HIP_MEMORY_SCOPE_AGENT); }
; __device__ __forceinline__ unsigned xb_add(unsigned* p, unsigned v) { return __hip_atomic_fetch_add(p, v, __ATOMIC_RELAXED, __HIP_MEMORY_SCOPE_AGENT); }
; #define XB_SPIN(cond, bar) do { unsigned _sp = 0; while (cond) { __builtin_amdgcn_s_sleep(1); \
;     if ((++_sp & 255u) == 0u) { if (xb_ld(&(bar)[XB_TMO])) break; if (_sp > XB_SPIN_CAP) { atomicAdd(&(bar)[XB_TMO], 1u); break; } } } } while (0)
; __device__ __forceinline__ void xcd_barrier(const XcdBarrier& b, int wave) {
;     asm volatile("s_waitcnt vmcnt(0)" ::: "memory");
;     __syncthreads();
;     if (ltid(wave) == 0) {
;         unsigned* bar = b.bar;
;         __builtin_amdgcn_s_waitcnt(0);
;         unsigned nloc = b.st[0], nx = b.st[1];
;         if (nloc == 0u) { xcd_barrier_complete(bar, b.x, nloc, nx); b.st[0] = nloc; b.st[1] = nx; }
;         const unsigned old = xb_add(&bar[XB_XSUB(b.x)], 1u);
;         const unsigned gen = old / nloc;
;         if (old + 1u == (gen + 1u) * nloc) {
;             __builtin_amdgcn_fence(__ATOMIC_RELEASE, "agent");
;             asm volatile("s_waitcnt vmcnt(0)" ::: "memory");
;             const unsigned og = xb_add(&bar[XB_TOP], 1u);
;             const unsigned tg = og / nx;
;             if (og + 1u == (tg + 1u) * nx) xb_add(&bar[XB_TOPGEN], 1u);
;             else XB_SPIN(xb_ld(&bar[XB_TOPGEN]) == tg, bar);
;             __builtin_amdgcn_fence(__ATOMIC_ACQUIRE, "agent");
;             xb_add(&bar[XB_XGEN(b.x)], 1u);
;             asm volatile("s_waitcnt vmcnt(0)" ::: "memory");
;         } else {
;             XB_SPIN(xb_ld(&bar[XB_XGEN(b.x)]) == gen, bar);
;             __builtin_amdgcn_fence(__ATOMIC_ACQUIRE, "agent");
;             asm volatile("s_waitcnt vmcnt(0)" ::: "memory");
;         }
;     }
;     __syncthreads();
; }
.LBB0_1071:
	v_readlane_b32 s0, v253, 51
	v_readlane_b32 s1, v253, 52
	v_cvt_f32_u32_e32 v0, v3
	v_sub_u32_e32 v5, 0, v3
	v_rcp_iflag_f32_e32 v0, v0
	s_nop 1
	global_atomic_add v4, v1, v224, s[0:1] sc0
	v_mul_f32_e32 v0, 0x4f7ffffe, v0
	v_cvt_u32_f32_e32 v0, v0
	v_mul_lo_u32 v5, v5, v0
	v_mul_hi_u32 v5, v0, v5
	v_add_u32_e32 v0, v0, v5
	s_waitcnt vmcnt(0)
	v_mul_hi_u32 v0, v4, v0
	v_mul_lo_u32 v5, v0, v3
	v_sub_u32_e32 v5, v4, v5
	v_add_u32_e32 v6, 1, v0
	v_cmp_ge_u32_e32 vcc, v5, v3
	v_add_u32_e32 v4, 1, v4
	s_nop 0
	v_cndmask_b32_e32 v0, v0, v6, vcc
	v_sub_u32_e32 v6, v5, v3
	v_cndmask_b32_e32 v5, v5, v6, vcc
	v_add_u32_e32 v6, 1, v0
	v_cmp_ge_u32_e32 vcc, v5, v3
	s_nop 1
	v_cndmask_b32_e32 v0, v0, v6, vcc
	v_mul_lo_u32 v5, v3, v0
	v_add_u32_e32 v3, v5, v3
	v_cmp_ne_u32_e32 vcc, v4, v3
	s_waitcnt lgkmcnt(0)
	v_add_u32_e32 v6, 1, v0
	v_mul_lo_u32 v7, v6, v2
	s_cbranch_vccnz .Lxb_wait
	buffer_wbl2 sc1
	s_waitcnt vmcnt(0)
	v_readlane_b32 s0, v252, 51
	v_readlane_b32 s1, v252, 52
	v_mov_b32_e32 v4, 0x2000
	s_nop 4
	global_atomic_add v4, v224, s[0:1]
	global_atomic_add v4, v224, s[0:1] offset:256
	global_atomic_add v4, v224, s[0:1] offset:512
	global_atomic_add v4, v224, s[0:1] offset:768
	global_atomic_add v4, v224, s[0:1] offset:1024
	global_atomic_add v4, v224, s[0:1] offset:1280
	global_atomic_add v4, v224, s[0:1] offset:1536
	global_atomic_add v4, v224, s[0:1] offset:1792
	global_atomic_add v4, v224, s[0:1] offset:2048
	global_atomic_add v4, v224, s[0:1] offset:2304
	global_atomic_add v4, v224, s[0:1] offset:2560
	global_atomic_add v4, v224, s[0:1] offset:2816
	global_atomic_add v4, v224, s[0:1] offset:3072
	global_atomic_add v4, v224, s[0:1] offset:3328
	global_atomic_add v4, v224, s[0:1] offset:3584
	global_atomic_add v4, v224, s[0:1] offset:3840
.Lxb_wait:
	v_readlane_b32 s4, v253, 53
	v_readlane_b32 s5, v253, 54
	s_mov_b32 s2, 0
	s_nop 4
.Lxb_spin:
	global_load_dword v2, v1, s[4:5] sc1
	s_waitcnt vmcnt(0)
	v_cmp_ge_u32_e32 vcc, v2, v7
	s_cbranch_vccnz .Lxb_done
	s_sleep 1
	s_add_i32 s2, s2, 1
	s_and_b32 s3, s2, 0xff
	s_cmp_lg_u32 s3, 0
	s_cbranch_scc1 .Lxb_spin
	v_readlane_b32 s6, v252, 49
	v_readlane_b32 s7, v252, 50
	s_nop 4
	global_load_dword v2, v1, s[6:7] sc1
	s_waitcnt vmcnt(0)
	v_cmp_ne_u32_e32 vcc, 0, v2
	s_cbranch_vccnz .Lxb_done
	s_cmp_lt_u32 s2, 0x40001
	s_cbranch_scc1 .Lxb_spin
	global_atomic_add v1, v224, s[6:7]
.Lxb_done:
	s_waitcnt vmcnt(0)
	buffer_inv sc1
	s_waitcnt vmcnt(0)
